# attention: PV MFMAs of the first half interleaved with the second half's softmax; waves 4-7 defer 16 PV MFMAs
# speedup vs baseline: 1.0114x; 1.0003x over previous
.Lnd_107:
	s_and_b32 s33, s42, 1
	s_mul_i32 s6, s33, 0x9000
	v_add_u32_e32 v199, s6, v187
	v_add_u32_e32 v198, s6, v188
	s_mov_b64 s[54:55], exec
	v_readfirstlane_b32 s4, v186
	s_bitcmp1_b32 s4, 8
	s_cbranch_scc1 .Lab_B
	ds_read_b128 v[216:219], v199 offset:0
	ds_read_b128 v[232:235], v193 offset:0
	ds_read_b128 v[220:223], v199 offset:32
	ds_read_b128 v[236:239], v193 offset:32
	ds_read_b128 v[224:227], v199 offset:64
	ds_read_b128 v[244:247], v193 offset:64
	ds_read_b128 v[228:231], v199 offset:96
	ds_read_b128 v[248:251], v193 offset:96
	s_waitcnt lgkmcnt(6)
	v_mfma_f32_32x32x16_bf16 v[144:159], v[216:219], v[232:235], v[0:15]
	s_waitcnt lgkmcnt(4)
	v_mfma_f32_32x32x16_bf16 v[144:159], v[220:223], v[236:239], v[144:159]
	s_waitcnt lgkmcnt(2)
	v_mfma_f32_32x32x16_bf16 v[144:159], v[224:227], v[244:247], v[144:159]
	s_waitcnt lgkmcnt(0)
	v_mfma_f32_32x32x16_bf16 v[144:159], v[228:231], v[248:251], v[144:159]
	ds_read_b128 v[216:219], v199 offset:9216
	ds_read_b128 v[232:235], v193 offset:36864
	ds_read_b128 v[220:223], v199 offset:9248
	ds_read_b128 v[236:239], v193 offset:36896
	ds_read_b128 v[224:227], v199 offset:9280
	ds_read_b128 v[244:247], v193 offset:36928
	ds_read_b128 v[228:231], v199 offset:9312
	ds_read_b128 v[248:251], v193 offset:36960
	s_nop 3
	v_exp_f32_e32 v144, v144
	v_exp_f32_e32 v145, v145
	v_exp_f32_e32 v146, v146
	v_exp_f32_e32 v147, v147
	v_exp_f32_e32 v148, v148
	v_exp_f32_e32 v149, v149
	v_exp_f32_e32 v150, v150
	v_exp_f32_e32 v151, v151
	v_exp_f32_e32 v152, v152
	v_exp_f32_e32 v153, v153
	v_exp_f32_e32 v154, v154
	v_exp_f32_e32 v155, v155
	v_exp_f32_e32 v156, v156
	v_exp_f32_e32 v157, v157
	v_exp_f32_e32 v158, v158
	v_exp_f32_e32 v159, v159
	v_add_f32_e32 v243, v144, v145
	v_add_f32_e32 v243, v146, v243
	v_add_f32_e32 v243, v147, v243
	v_add_f32_e32 v243, v148, v243
	v_add_f32_e32 v243, v149, v243
	v_add_f32_e32 v243, v150, v243
	v_add_f32_e32 v243, v151, v243
	s_waitcnt lgkmcnt(6)
	v_mfma_f32_32x32x16_bf16 v[200:215], v[216:219], v[232:235], v[0:15]
	s_waitcnt lgkmcnt(4)
	v_mfma_f32_32x32x16_bf16 v[200:215], v[220:223], v[236:239], v[200:215]
	s_waitcnt lgkmcnt(2)
	v_mfma_f32_32x32x16_bf16 v[200:215], v[224:227], v[244:247], v[200:215]
	s_waitcnt lgkmcnt(0)
	v_mfma_f32_32x32x16_bf16 v[200:215], v[228:231], v[248:251], v[200:215]
	ds_read_b128 v[216:219], v198 offset:0
	ds_read_b128 v[224:227], v198 offset:4608
	ds_read_b128 v[232:235], v198 offset:9216
	ds_read_b128 v[244:247], v198 offset:13824
	ds_read_b128 v[220:223], v198 offset:32
	ds_read_b128 v[228:231], v198 offset:4640
	ds_read_b128 v[236:239], v198 offset:9248
	ds_read_b128 v[248:251], v198 offset:13856
	v_add_f32_e32 v243, v152, v243
	v_add_f32_e32 v243, v153, v243
	v_add_f32_e32 v243, v154, v243
	v_add_f32_e32 v243, v155, v243
	v_add_f32_e32 v243, v156, v243
	v_add_f32_e32 v243, v157, v243
	v_add_f32_e32 v243, v158, v243
	v_add_f32_e32 v243, v159, v243
	v_add_f32_e32 v196, v196, v243
	v_cvt_pk_bf16_f32 v144, v144, v145
	v_cvt_pk_bf16_f32 v145, v146, v147
	v_cvt_pk_bf16_f32 v146, v148, v149
	v_cvt_pk_bf16_f32 v147, v150, v151
	v_cvt_pk_bf16_f32 v148, v152, v153
	v_cvt_pk_bf16_f32 v149, v154, v155
	v_cvt_pk_bf16_f32 v150, v156, v157
	v_cvt_pk_bf16_f32 v151, v158, v159
	s_waitcnt lgkmcnt(7)
	v_mfma_f32_32x32x16_bf16 v[112:127], v[216:219], v[144:147], v[112:127]
	v_exp_f32_e32 v200, v200
	v_exp_f32_e32 v201, v201
	v_exp_f32_e32 v202, v202
	v_exp_f32_e32 v203, v203
	v_exp_f32_e32 v204, v204
	s_waitcnt lgkmcnt(6)
	v_mfma_f32_32x32x16_bf16 v[80:95], v[224:227], v[144:147], v[80:95]
	v_exp_f32_e32 v205, v205
	v_exp_f32_e32 v206, v206
	v_exp_f32_e32 v207, v207
	v_exp_f32_e32 v208, v208
	v_exp_f32_e32 v209, v209
	s_waitcnt lgkmcnt(5)
	v_mfma_f32_32x32x16_bf16 v[48:63], v[232:235], v[144:147], v[48:63]
	v_exp_f32_e32 v210, v210
	v_exp_f32_e32 v211, v211
	v_exp_f32_e32 v212, v212
	v_exp_f32_e32 v213, v213
	v_exp_f32_e32 v214, v214
	s_waitcnt lgkmcnt(4)
	v_mfma_f32_32x32x16_bf16 v[16:31], v[244:247], v[144:147], v[16:31]
	v_exp_f32_e32 v215, v215
	v_add_f32_e32 v243, v200, v201
	v_add_f32_e32 v243, v202, v243
	v_add_f32_e32 v243, v203, v243
	v_add_f32_e32 v243, v204, v243
	s_waitcnt lgkmcnt(3)
	v_mfma_f32_32x32x16_bf16 v[112:127], v[220:223], v[148:151], v[112:127]
	v_add_f32_e32 v243, v205, v243
	v_add_f32_e32 v243, v206, v243
	v_add_f32_e32 v243, v207, v243
	v_add_f32_e32 v243, v208, v243
	v_add_f32_e32 v243, v209, v243
	s_waitcnt lgkmcnt(2)
	v_mfma_f32_32x32x16_bf16 v[80:95], v[228:231], v[148:151], v[80:95]
	v_add_f32_e32 v243, v210, v243
	v_add_f32_e32 v243, v211, v243
	v_add_f32_e32 v243, v212, v243
	v_add_f32_e32 v243, v213, v243
	v_add_f32_e32 v243, v214, v243
	s_waitcnt lgkmcnt(1)
	v_mfma_f32_32x32x16_bf16 v[48:63], v[236:239], v[148:151], v[48:63]
	v_add_f32_e32 v243, v215, v243
	v_add_f32_e32 v197, v197, v243
	v_cvt_pk_bf16_f32 v200, v200, v201
	v_cvt_pk_bf16_f32 v201, v202, v203
	v_cvt_pk_bf16_f32 v202, v204, v205
	s_waitcnt lgkmcnt(0)
	v_mfma_f32_32x32x16_bf16 v[16:31], v[248:251], v[148:151], v[16:31]
	v_cvt_pk_bf16_f32 v203, v206, v207
	v_cvt_pk_bf16_f32 v204, v208, v209
	v_cvt_pk_bf16_f32 v205, v210, v211
	v_cvt_pk_bf16_f32 v206, v212, v213
	v_cvt_pk_bf16_f32 v207, v214, v215
	s_nop 1
	v_mfma_f32_32x32x16_bf16 v[128:143], v[216:219], v[200:203], v[128:143]
	v_mfma_f32_32x32x16_bf16 v[96:111], v[224:227], v[200:203], v[96:111]
	v_mfma_f32_32x32x16_bf16 v[64:79], v[232:235], v[200:203], v[64:79]
	v_mfma_f32_32x32x16_bf16 v[32:47], v[244:247], v[200:203], v[32:47]
	v_mfma_f32_32x32x16_bf16 v[128:143], v[220:223], v[204:207], v[128:143]
	v_mfma_f32_32x32x16_bf16 v[96:111], v[228:231], v[204:207], v[96:111]
	v_mfma_f32_32x32x16_bf16 v[64:79], v[236:239], v[204:207], v[64:79]
	v_mfma_f32_32x32x16_bf16 v[32:47], v[248:251], v[204:207], v[32:47]
	ds_read_b128 v[216:219], v199 offset:4608
	ds_read_b128 v[232:235], v193 offset:0
	ds_read_b128 v[220:223], v199 offset:4640
	ds_read_b128 v[236:239], v193 offset:32
	ds_read_b128 v[224:227], v199 offset:4672
	ds_read_b128 v[244:247], v193 offset:64
	ds_read_b128 v[228:231], v199 offset:4704
	ds_read_b128 v[248:251], v193 offset:96
	s_waitcnt lgkmcnt(6)
	v_mfma_f32_32x32x16_bf16 v[144:159], v[216:219], v[232:235], v[0:15]
	s_waitcnt lgkmcnt(4)
	v_mfma_f32_32x32x16_bf16 v[144:159], v[220:223], v[236:239], v[144:159]
	s_waitcnt lgkmcnt(2)
	v_mfma_f32_32x32x16_bf16 v[144:159], v[224:227], v[244:247], v[144:159]
	s_waitcnt lgkmcnt(0)
	v_mfma_f32_32x32x16_bf16 v[144:159], v[228:231], v[248:251], v[144:159]
	ds_read_b128 v[216:219], v199 offset:13824
	ds_read_b128 v[232:235], v193 offset:36864
	ds_read_b128 v[220:223], v199 offset:13856
	ds_read_b128 v[236:239], v193 offset:36896
	ds_read_b128 v[224:227], v199 offset:13888
	ds_read_b128 v[244:247], v193 offset:36928
	ds_read_b128 v[228:231], v199 offset:13920
	ds_read_b128 v[248:251], v193 offset:36960
	s_nop 3
	v_exp_f32_e32 v144, v144
	v_exp_f32_e32 v145, v145
	v_exp_f32_e32 v146, v146
	v_exp_f32_e32 v147, v147
	v_exp_f32_e32 v148, v148
	v_exp_f32_e32 v149, v149
	v_exp_f32_e32 v150, v150
	v_exp_f32_e32 v151, v151
	v_exp_f32_e32 v152, v152
	v_exp_f32_e32 v153, v153
	v_exp_f32_e32 v154, v154
	v_exp_f32_e32 v155, v155
	v_exp_f32_e32 v156, v156
	v_exp_f32_e32 v157, v157
	v_exp_f32_e32 v158, v158
	v_exp_f32_e32 v159, v159
	v_add_f32_e32 v243, v144, v145
	v_add_f32_e32 v243, v146, v243
	v_add_f32_e32 v243, v147, v243
	v_add_f32_e32 v243, v148, v243
	v_add_f32_e32 v243, v149, v243
	v_add_f32_e32 v243, v150, v243
	v_add_f32_e32 v243, v151, v243
	s_waitcnt lgkmcnt(6)
	v_mfma_f32_32x32x16_bf16 v[200:215], v[216:219], v[232:235], v[0:15]
	s_waitcnt lgkmcnt(4)
	v_mfma_f32_32x32x16_bf16 v[200:215], v[220:223], v[236:239], v[200:215]
	s_waitcnt lgkmcnt(2)
	v_mfma_f32_32x32x16_bf16 v[200:215], v[224:227], v[244:247], v[200:215]
	s_waitcnt lgkmcnt(0)
	v_mfma_f32_32x32x16_bf16 v[200:215], v[228:231], v[248:251], v[200:215]
	ds_read_b128 v[216:219], v198 offset:64
	ds_read_b128 v[224:227], v198 offset:4672
	ds_read_b128 v[232:235], v198 offset:9280
	ds_read_b128 v[244:247], v198 offset:13888
	ds_read_b128 v[220:223], v198 offset:96
	ds_read_b128 v[228:231], v198 offset:4704
	ds_read_b128 v[236:239], v198 offset:9312
	ds_read_b128 v[248:251], v198 offset:13920
	v_add_f32_e32 v243, v152, v243
	v_add_f32_e32 v243, v153, v243
	v_add_f32_e32 v243, v154, v243
	v_add_f32_e32 v243, v155, v243
	v_add_f32_e32 v243, v156, v243
	v_add_f32_e32 v243, v157, v243
	v_add_f32_e32 v243, v158, v243
	v_add_f32_e32 v243, v159, v243
	v_add_f32_e32 v196, v196, v243
	v_cvt_pk_bf16_f32 v144, v144, v145
	v_cvt_pk_bf16_f32 v145, v146, v147
	v_cvt_pk_bf16_f32 v146, v148, v149
	v_cvt_pk_bf16_f32 v147, v150, v151
	v_cvt_pk_bf16_f32 v148, v152, v153
	v_cvt_pk_bf16_f32 v149, v154, v155
	v_cvt_pk_bf16_f32 v150, v156, v157
	v_cvt_pk_bf16_f32 v151, v158, v159
	s_waitcnt lgkmcnt(7)
	v_mfma_f32_32x32x16_bf16 v[112:127], v[216:219], v[144:147], v[112:127]
	v_exp_f32_e32 v200, v200
	v_exp_f32_e32 v201, v201
	v_exp_f32_e32 v202, v202
	v_exp_f32_e32 v203, v203
	v_exp_f32_e32 v204, v204
	s_waitcnt lgkmcnt(6)
	v_mfma_f32_32x32x16_bf16 v[80:95], v[224:227], v[144:147], v[80:95]
	v_exp_f32_e32 v205, v205
	v_exp_f32_e32 v206, v206
	v_exp_f32_e32 v207, v207
	v_exp_f32_e32 v208, v208
	v_exp_f32_e32 v209, v209
	s_waitcnt lgkmcnt(5)
	v_mfma_f32_32x32x16_bf16 v[48:63], v[232:235], v[144:147], v[48:63]
	v_exp_f32_e32 v210, v210
	v_exp_f32_e32 v211, v211
	v_exp_f32_e32 v212, v212
	v_exp_f32_e32 v213, v213
	v_exp_f32_e32 v214, v214
	s_waitcnt lgkmcnt(4)
	v_mfma_f32_32x32x16_bf16 v[16:31], v[244:247], v[144:147], v[16:31]
	v_exp_f32_e32 v215, v215
	v_add_f32_e32 v243, v200, v201
	v_add_f32_e32 v243, v202, v243
	v_add_f32_e32 v243, v203, v243
	v_add_f32_e32 v243, v204, v243
	s_waitcnt lgkmcnt(3)
	v_mfma_f32_32x32x16_bf16 v[112:127], v[220:223], v[148:151], v[112:127]
	v_add_f32_e32 v243, v205, v243
	v_add_f32_e32 v243, v206, v243
	v_add_f32_e32 v243, v207, v243
	v_add_f32_e32 v243, v208, v243
	v_add_f32_e32 v243, v209, v243
	s_waitcnt lgkmcnt(2)
	v_mfma_f32_32x32x16_bf16 v[80:95], v[228:231], v[148:151], v[80:95]
	v_add_f32_e32 v243, v210, v243
	v_add_f32_e32 v243, v211, v243
	v_add_f32_e32 v243, v212, v243
	v_add_f32_e32 v243, v213, v243
	v_add_f32_e32 v243, v214, v243
	s_waitcnt lgkmcnt(1)
	v_mfma_f32_32x32x16_bf16 v[48:63], v[236:239], v[148:151], v[48:63]
	v_add_f32_e32 v243, v215, v243
	v_add_f32_e32 v197, v197, v243
	v_cvt_pk_bf16_f32 v200, v200, v201
	v_cvt_pk_bf16_f32 v201, v202, v203
	v_cvt_pk_bf16_f32 v202, v204, v205
	s_waitcnt lgkmcnt(0)
	v_mfma_f32_32x32x16_bf16 v[16:31], v[248:251], v[148:151], v[16:31]
	v_cvt_pk_bf16_f32 v203, v206, v207
	v_cvt_pk_bf16_f32 v204, v208, v209
	v_cvt_pk_bf16_f32 v205, v210, v211
	v_cvt_pk_bf16_f32 v206, v212, v213
	v_cvt_pk_bf16_f32 v207, v214, v215
	s_nop 1
	v_mfma_f32_32x32x16_bf16 v[128:143], v[216:219], v[200:203], v[128:143]
	v_mfma_f32_32x32x16_bf16 v[96:111], v[224:227], v[200:203], v[96:111]
	v_mfma_f32_32x32x16_bf16 v[64:79], v[232:235], v[200:203], v[64:79]
	v_mfma_f32_32x32x16_bf16 v[32:47], v[244:247], v[200:203], v[32:47]
	v_mfma_f32_32x32x16_bf16 v[128:143], v[220:223], v[204:207], v[128:143]
	v_mfma_f32_32x32x16_bf16 v[96:111], v[228:231], v[204:207], v[96:111]
	v_mfma_f32_32x32x16_bf16 v[64:79], v[236:239], v[204:207], v[64:79]
	v_mfma_f32_32x32x16_bf16 v[32:47], v[248:251], v[204:207], v[32:47]
	s_branch .LBB0_111
.Lab_B:
	s_cmp_eq_u32 s42, 0
	s_cbranch_scc1 .Lab_B0
	v_mfma_f32_32x32x16_bf16 v[112:127], v[216:219], v[144:147], v[112:127]
	v_mfma_f32_32x32x16_bf16 v[80:95], v[224:227], v[144:147], v[80:95]
	v_mfma_f32_32x32x16_bf16 v[48:63], v[232:235], v[144:147], v[48:63]
	v_mfma_f32_32x32x16_bf16 v[16:31], v[244:247], v[144:147], v[16:31]
	v_mfma_f32_32x32x16_bf16 v[112:127], v[220:223], v[148:151], v[112:127]
	v_mfma_f32_32x32x16_bf16 v[80:95], v[228:231], v[148:151], v[80:95]
	v_mfma_f32_32x32x16_bf16 v[48:63], v[236:239], v[148:151], v[48:63]
	v_mfma_f32_32x32x16_bf16 v[16:31], v[248:251], v[148:151], v[16:31]
	v_mfma_f32_32x32x16_bf16 v[128:143], v[216:219], v[200:203], v[128:143]
	v_mfma_f32_32x32x16_bf16 v[96:111], v[224:227], v[200:203], v[96:111]
	v_mfma_f32_32x32x16_bf16 v[64:79], v[232:235], v[200:203], v[64:79]
	v_mfma_f32_32x32x16_bf16 v[32:47], v[244:247], v[200:203], v[32:47]
	v_mfma_f32_32x32x16_bf16 v[128:143], v[220:223], v[204:207], v[128:143]
	v_mfma_f32_32x32x16_bf16 v[96:111], v[228:231], v[204:207], v[96:111]
	v_mfma_f32_32x32x16_bf16 v[64:79], v[236:239], v[204:207], v[64:79]
	v_mfma_f32_32x32x16_bf16 v[32:47], v[248:251], v[204:207], v[32:47]
.Lab_B0:
	ds_read_b128 v[216:219], v199 offset:0
	ds_read_b128 v[232:235], v193 offset:0
	ds_read_b128 v[220:223], v199 offset:32
	ds_read_b128 v[236:239], v193 offset:32
	ds_read_b128 v[224:227], v199 offset:64
	ds_read_b128 v[244:247], v193 offset:64
	ds_read_b128 v[228:231], v199 offset:96
	ds_read_b128 v[248:251], v193 offset:96
	s_waitcnt lgkmcnt(6)
	v_mfma_f32_32x32x16_bf16 v[144:159], v[216:219], v[232:235], v[0:15]
	s_waitcnt lgkmcnt(4)
	v_mfma_f32_32x32x16_bf16 v[144:159], v[220:223], v[236:239], v[144:159]
	s_waitcnt lgkmcnt(2)
	v_mfma_f32_32x32x16_bf16 v[144:159], v[224:227], v[244:247], v[144:159]
	s_waitcnt lgkmcnt(0)
	v_mfma_f32_32x32x16_bf16 v[144:159], v[228:231], v[248:251], v[144:159]
	ds_read_b128 v[216:219], v199 offset:9216
	ds_read_b128 v[232:235], v193 offset:36864
	ds_read_b128 v[220:223], v199 offset:9248
	ds_read_b128 v[236:239], v193 offset:36896
	ds_read_b128 v[224:227], v199 offset:9280
	ds_read_b128 v[244:247], v193 offset:36928
	ds_read_b128 v[228:231], v199 offset:9312
	ds_read_b128 v[248:251], v193 offset:36960
	s_nop 3
	v_exp_f32_e32 v144, v144
	v_exp_f32_e32 v145, v145
	v_exp_f32_e32 v146, v146
	v_exp_f32_e32 v147, v147
	v_exp_f32_e32 v148, v148
	v_exp_f32_e32 v149, v149
	v_exp_f32_e32 v150, v150
	v_exp_f32_e32 v151, v151
	v_exp_f32_e32 v152, v152
	v_exp_f32_e32 v153, v153
	v_exp_f32_e32 v154, v154
	v_exp_f32_e32 v155, v155
	v_exp_f32_e32 v156, v156
	v_exp_f32_e32 v157, v157
	v_exp_f32_e32 v158, v158
	v_exp_f32_e32 v159, v159
	v_add_f32_e32 v243, v144, v145
	v_add_f32_e32 v243, v146, v243
	v_add_f32_e32 v243, v147, v243
	v_add_f32_e32 v243, v148, v243
	v_add_f32_e32 v243, v149, v243
	v_add_f32_e32 v243, v150, v243
	v_add_f32_e32 v243, v151, v243
	s_waitcnt lgkmcnt(6)
	v_mfma_f32_32x32x16_bf16 v[200:215], v[216:219], v[232:235], v[0:15]
	s_waitcnt lgkmcnt(4)
	v_mfma_f32_32x32x16_bf16 v[200:215], v[220:223], v[236:239], v[200:215]
	s_waitcnt lgkmcnt(2)
	v_mfma_f32_32x32x16_bf16 v[200:215], v[224:227], v[244:247], v[200:215]
	s_waitcnt lgkmcnt(0)
	v_mfma_f32_32x32x16_bf16 v[200:215], v[228:231], v[248:251], v[200:215]
	ds_read_b128 v[216:219], v198 offset:0
	ds_read_b128 v[224:227], v198 offset:4608
	ds_read_b128 v[232:235], v198 offset:9216
	ds_read_b128 v[244:247], v198 offset:13824
	ds_read_b128 v[220:223], v198 offset:32
	ds_read_b128 v[228:231], v198 offset:4640
	ds_read_b128 v[236:239], v198 offset:9248
	ds_read_b128 v[248:251], v198 offset:13856
	v_add_f32_e32 v243, v152, v243
	v_add_f32_e32 v243, v153, v243
	v_add_f32_e32 v243, v154, v243
	v_add_f32_e32 v243, v155, v243
	v_add_f32_e32 v243, v156, v243
	v_add_f32_e32 v243, v157, v243
	v_add_f32_e32 v243, v158, v243
	v_add_f32_e32 v243, v159, v243
	v_add_f32_e32 v196, v196, v243
	v_cvt_pk_bf16_f32 v144, v144, v145
	v_cvt_pk_bf16_f32 v145, v146, v147
	v_cvt_pk_bf16_f32 v146, v148, v149
	v_cvt_pk_bf16_f32 v147, v150, v151
	v_cvt_pk_bf16_f32 v148, v152, v153
	v_cvt_pk_bf16_f32 v149, v154, v155
	v_cvt_pk_bf16_f32 v150, v156, v157
	v_cvt_pk_bf16_f32 v151, v158, v159
	s_waitcnt lgkmcnt(7)
	v_mfma_f32_32x32x16_bf16 v[112:127], v[216:219], v[144:147], v[112:127]
	v_exp_f32_e32 v200, v200
	v_exp_f32_e32 v201, v201
	v_exp_f32_e32 v202, v202
	v_exp_f32_e32 v203, v203
	v_exp_f32_e32 v204, v204
	s_waitcnt lgkmcnt(6)
	v_mfma_f32_32x32x16_bf16 v[80:95], v[224:227], v[144:147], v[80:95]
	v_exp_f32_e32 v205, v205
	v_exp_f32_e32 v206, v206
	v_exp_f32_e32 v207, v207
	v_exp_f32_e32 v208, v208
	v_exp_f32_e32 v209, v209
	s_waitcnt lgkmcnt(5)
	v_mfma_f32_32x32x16_bf16 v[48:63], v[232:235], v[144:147], v[48:63]
	v_exp_f32_e32 v210, v210
	v_exp_f32_e32 v211, v211
	v_exp_f32_e32 v212, v212
	v_exp_f32_e32 v213, v213
	v_exp_f32_e32 v214, v214
	s_waitcnt lgkmcnt(4)
	v_mfma_f32_32x32x16_bf16 v[16:31], v[244:247], v[144:147], v[16:31]
	v_exp_f32_e32 v215, v215
	v_add_f32_e32 v243, v200, v201
	v_add_f32_e32 v243, v202, v243
	v_add_f32_e32 v243, v203, v243
	v_add_f32_e32 v243, v204, v243
	s_waitcnt lgkmcnt(3)
	v_mfma_f32_32x32x16_bf16 v[112:127], v[220:223], v[148:151], v[112:127]
	v_add_f32_e32 v243, v205, v243
	v_add_f32_e32 v243, v206, v243
	v_add_f32_e32 v243, v207, v243
	v_add_f32_e32 v243, v208, v243
	v_add_f32_e32 v243, v209, v243
	s_waitcnt lgkmcnt(2)
	v_mfma_f32_32x32x16_bf16 v[80:95], v[228:231], v[148:151], v[80:95]
	v_add_f32_e32 v243, v210, v243
	v_add_f32_e32 v243, v211, v243
	v_add_f32_e32 v243, v212, v243
	v_add_f32_e32 v243, v213, v243
	v_add_f32_e32 v243, v214, v243
	s_waitcnt lgkmcnt(1)
	v_mfma_f32_32x32x16_bf16 v[48:63], v[236:239], v[148:151], v[48:63]
	v_add_f32_e32 v243, v215, v243
	v_add_f32_e32 v197, v197, v243
	v_cvt_pk_bf16_f32 v200, v200, v201
	v_cvt_pk_bf16_f32 v201, v202, v203
	v_cvt_pk_bf16_f32 v202, v204, v205
	s_waitcnt lgkmcnt(0)
	v_mfma_f32_32x32x16_bf16 v[16:31], v[248:251], v[148:151], v[16:31]
	v_cvt_pk_bf16_f32 v203, v206, v207
	v_cvt_pk_bf16_f32 v204, v208, v209
	v_cvt_pk_bf16_f32 v205, v210, v211
	v_cvt_pk_bf16_f32 v206, v212, v213
	v_cvt_pk_bf16_f32 v207, v214, v215
	s_nop 1
	v_mfma_f32_32x32x16_bf16 v[128:143], v[216:219], v[200:203], v[128:143]
	v_mfma_f32_32x32x16_bf16 v[96:111], v[224:227], v[200:203], v[96:111]
	v_mfma_f32_32x32x16_bf16 v[64:79], v[232:235], v[200:203], v[64:79]
	v_mfma_f32_32x32x16_bf16 v[32:47], v[244:247], v[200:203], v[32:47]
	v_mfma_f32_32x32x16_bf16 v[128:143], v[220:223], v[204:207], v[128:143]
	v_mfma_f32_32x32x16_bf16 v[96:111], v[228:231], v[204:207], v[96:111]
	v_mfma_f32_32x32x16_bf16 v[64:79], v[236:239], v[204:207], v[64:79]
	v_mfma_f32_32x32x16_bf16 v[32:47], v[248:251], v[204:207], v[32:47]
	ds_read_b128 v[216:219], v199 offset:4608
	ds_read_b128 v[232:235], v193 offset:0
	ds_read_b128 v[220:223], v199 offset:4640
	ds_read_b128 v[236:239], v193 offset:32
	ds_read_b128 v[224:227], v199 offset:4672
	ds_read_b128 v[244:247], v193 offset:64
	ds_read_b128 v[228:231], v199 offset:4704
	ds_read_b128 v[248:251], v193 offset:96
	s_waitcnt lgkmcnt(6)
	v_mfma_f32_32x32x16_bf16 v[144:159], v[216:219], v[232:235], v[0:15]
	s_waitcnt lgkmcnt(4)
	v_mfma_f32_32x32x16_bf16 v[144:159], v[220:223], v[236:239], v[144:159]
	s_waitcnt lgkmcnt(2)
	v_mfma_f32_32x32x16_bf16 v[144:159], v[224:227], v[244:247], v[144:159]
	s_waitcnt lgkmcnt(0)
	v_mfma_f32_32x32x16_bf16 v[144:159], v[228:231], v[248:251], v[144:159]
	ds_read_b128 v[216:219], v199 offset:13824
	ds_read_b128 v[232:235], v193 offset:36864
	ds_read_b128 v[220:223], v199 offset:13856
	ds_read_b128 v[236:239], v193 offset:36896
	ds_read_b128 v[224:227], v199 offset:13888
	ds_read_b128 v[244:247], v193 offset:36928
	ds_read_b128 v[228:231], v199 offset:13920
	ds_read_b128 v[248:251], v193 offset:36960
	s_nop 3
	v_exp_f32_e32 v144, v144
	v_exp_f32_e32 v145, v145
	v_exp_f32_e32 v146, v146
	v_exp_f32_e32 v147, v147
	v_exp_f32_e32 v148, v148
	v_exp_f32_e32 v149, v149
	v_exp_f32_e32 v150, v150
	v_exp_f32_e32 v151, v151
	v_exp_f32_e32 v152, v152
	v_exp_f32_e32 v153, v153
	v_exp_f32_e32 v154, v154
	v_exp_f32_e32 v155, v155
	v_exp_f32_e32 v156, v156
	v_exp_f32_e32 v157, v157
	v_exp_f32_e32 v158, v158
	v_exp_f32_e32 v159, v159
	v_add_f32_e32 v243, v144, v145
	v_add_f32_e32 v243, v146, v243
	v_add_f32_e32 v243, v147, v243
	v_add_f32_e32 v243, v148, v243
	v_add_f32_e32 v243, v149, v243
	v_add_f32_e32 v243, v150, v243
	v_add_f32_e32 v243, v151, v243
	s_waitcnt lgkmcnt(6)
	v_mfma_f32_32x32x16_bf16 v[200:215], v[216:219], v[232:235], v[0:15]
	s_waitcnt lgkmcnt(4)
	v_mfma_f32_32x32x16_bf16 v[200:215], v[220:223], v[236:239], v[200:215]
	s_waitcnt lgkmcnt(2)
	v_mfma_f32_32x32x16_bf16 v[200:215], v[224:227], v[244:247], v[200:215]
	s_waitcnt lgkmcnt(0)
	v_mfma_f32_32x32x16_bf16 v[200:215], v[228:231], v[248:251], v[200:215]
	ds_read_b128 v[216:219], v198 offset:64
	ds_read_b128 v[224:227], v198 offset:4672
	ds_read_b128 v[232:235], v198 offset:9280
	ds_read_b128 v[244:247], v198 offset:13888
	ds_read_b128 v[220:223], v198 offset:96
	ds_read_b128 v[228:231], v198 offset:4704
	ds_read_b128 v[236:239], v198 offset:9312
	ds_read_b128 v[248:251], v198 offset:13920
	v_add_f32_e32 v243, v152, v243
	v_add_f32_e32 v243, v153, v243
	v_add_f32_e32 v243, v154, v243
	v_add_f32_e32 v243, v155, v243
	v_add_f32_e32 v243, v156, v243
	v_add_f32_e32 v243, v157, v243
	v_add_f32_e32 v243, v158, v243
	v_add_f32_e32 v243, v159, v243
	v_add_f32_e32 v196, v196, v243
	v_cvt_pk_bf16_f32 v144, v144, v145
	v_cvt_pk_bf16_f32 v145, v146, v147
	v_cvt_pk_bf16_f32 v146, v148, v149
	v_cvt_pk_bf16_f32 v147, v150, v151
	v_cvt_pk_bf16_f32 v148, v152, v153
	v_cvt_pk_bf16_f32 v149, v154, v155
	v_cvt_pk_bf16_f32 v150, v156, v157
	v_cvt_pk_bf16_f32 v151, v158, v159
	v_exp_f32_e32 v200, v200
	v_exp_f32_e32 v201, v201
	v_exp_f32_e32 v202, v202
	v_exp_f32_e32 v203, v203
	v_exp_f32_e32 v204, v204
	v_exp_f32_e32 v205, v205
	v_exp_f32_e32 v206, v206
	v_exp_f32_e32 v207, v207
	v_exp_f32_e32 v208, v208
	v_exp_f32_e32 v209, v209
	v_exp_f32_e32 v210, v210
	v_exp_f32_e32 v211, v211
	v_exp_f32_e32 v212, v212
	v_exp_f32_e32 v213, v213
	v_exp_f32_e32 v214, v214
	v_exp_f32_e32 v215, v215
	v_add_f32_e32 v243, v200, v201
	v_add_f32_e32 v243, v202, v243
	v_add_f32_e32 v243, v203, v243
	v_add_f32_e32 v243, v204, v243
	v_add_f32_e32 v243, v205, v243
	v_add_f32_e32 v243, v206, v243
	v_add_f32_e32 v243, v207, v243
	v_add_f32_e32 v243, v208, v243
	v_add_f32_e32 v243, v209, v243
	v_add_f32_e32 v243, v210, v243
	v_add_f32_e32 v243, v211, v243
	v_add_f32_e32 v243, v212, v243
	v_add_f32_e32 v243, v213, v243
	v_add_f32_e32 v243, v214, v243
	v_add_f32_e32 v243, v215, v243
	v_add_f32_e32 v197, v197, v243
	v_cvt_pk_bf16_f32 v200, v200, v201
	v_cvt_pk_bf16_f32 v201, v202, v203
	v_cvt_pk_bf16_f32 v202, v204, v205
	v_cvt_pk_bf16_f32 v203, v206, v207
	v_cvt_pk_bf16_f32 v204, v208, v209
	v_cvt_pk_bf16_f32 v205, v210, v211
	v_cvt_pk_bf16_f32 v206, v212, v213
	v_cvt_pk_bf16_f32 v207, v214, v215
	s_add_i32 s4, s42, 1
	s_cmp_lt_u32 s4, s98
	s_cbranch_scc1 .LBB0_111
	s_waitcnt lgkmcnt(0)
	s_nop 1
	v_mfma_f32_32x32x16_bf16 v[112:127], v[216:219], v[144:147], v[112:127]
	v_mfma_f32_32x32x16_bf16 v[80:95], v[224:227], v[144:147], v[80:95]
	v_mfma_f32_32x32x16_bf16 v[48:63], v[232:235], v[144:147], v[48:63]
	v_mfma_f32_32x32x16_bf16 v[16:31], v[244:247], v[144:147], v[16:31]
	v_mfma_f32_32x32x16_bf16 v[112:127], v[220:223], v[148:151], v[112:127]
	v_mfma_f32_32x32x16_bf16 v[80:95], v[228:231], v[148:151], v[80:95]
	v_mfma_f32_32x32x16_bf16 v[48:63], v[236:239], v[148:151], v[48:63]
	v_mfma_f32_32x32x16_bf16 v[16:31], v[248:251], v[148:151], v[16:31]
	v_mfma_f32_32x32x16_bf16 v[128:143], v[216:219], v[200:203], v[128:143]
	v_mfma_f32_32x32x16_bf16 v[96:111], v[224:227], v[200:203], v[96:111]
	v_mfma_f32_32x32x16_bf16 v[64:79], v[232:235], v[200:203], v[64:79]
	v_mfma_f32_32x32x16_bf16 v[32:47], v[244:247], v[200:203], v[32:47]
	v_mfma_f32_32x32x16_bf16 v[128:143], v[220:223], v[204:207], v[128:143]
	v_mfma_f32_32x32x16_bf16 v[96:111], v[228:231], v[204:207], v[96:111]
	v_mfma_f32_32x32x16_bf16 v[64:79], v[236:239], v[204:207], v[64:79]
	v_mfma_f32_32x32x16_bf16 v[32:47], v[248:251], v[204:207], v[32:47]
	s_branch .LBB0_111
